# P4 combine rewritten: 4 items per trip, all 32 loads in flight with counted waits (was one load per wait)
# speedup vs baseline: 1.0111x; 1.0052x over previous
.LBB0_903:
	s_or_b64 exec, exec, s[0:1]
	s_waitcnt lgkmcnt(0)
	v_mov_b32_e32 v0, v192
	v_mov_b32_e32 v1, v192
	s_barrier
	s_mov_b32 s10, 0x200000
	v_add_u32_e32 v20, s46, v1
	v_cmp_gt_i32_e32 vcc, s10, v20
	s_and_saveexec_b64 s[0:1], vcc
	s_cbranch_execz .LBB0_920
	v_and_b32_e32 v0, 0x7f, v1
	v_lshlrev_b32_e32 v6, 4, v0
	v_mov_b32_e32 v0, 0
	v_lshrrev_b32_e32 v1, 2, v1
	v_and_b32_e32 v4, 28, v1
	v_mov_b32_e32 v5, v0
	v_mov_b32_e32 v7, v0
	v_lshl_add_u64 v[4:5], s[78:79], 0, v[4:5]
	s_mov_b64 s[2:3], 0x500000
	s_lshl_b32 s11, s88, 9
	v_lshl_add_u64 v[2:3], s[76:77], 0, v[6:7]
	v_lshl_add_u64 v[4:5], v[4:5], 0, s[2:3]
	v_lshl_add_u64 v[6:7], s[86:87], 0, v[6:7]
	s_mov_b64 s[2:3], 0
	s_mov_b32 s12, 0x1fffff
	s_mov_b64 s[6:7], 0x1000
	s_mov_b64 s[2:3], 0
.Lc4_outer:
	v_mov_b32_e32 v52, v20
	s_mov_b32 s12, s11
	v_cmp_gt_i32_e64 s[14:15], s10, v52
	v_mov_b32_e32 v55, 0
	s_nop 0
	v_cndmask_b32_e64 v52, v20, v52, s[14:15]
	v_ashrrev_i32_e32 v54, 7, v52
	v_ashrrev_i32_e32 v56, 15, v52
	v_lshlrev_b64 v[160:161], 13, v[54:55]
	v_lshlrev_b64 v[164:165], 7, v[54:55]
	v_lshl_add_u64 v[160:161], v[2:3], 0, v[160:161]
	v_lshl_add_u64 v[164:165], v[4:5], 0, v[164:165]
	v_lshl_add_u64 v[162:163], v[160:161], 0, s[6:7]
	global_load_dwordx4 v[32:35], v[160:161], off
	global_load_dword v48, v[164:165], off
	global_load_dwordx4 v[36:39], v[160:161], off offset:2048
	global_load_dword v49, v[164:165], off offset:32
	global_load_dwordx4 v[40:43], v[162:163], off
	global_load_dword v50, v[164:165], off offset:64
	global_load_dwordx4 v[44:47], v[162:163], off offset:2048
	global_load_dword v51, v[164:165], off offset:96
	v_add_u32_e32 v84, s12, v20
	s_add_i32 s12, s12, s11
	v_cmp_gt_i32_e64 s[16:17], s10, v84
	v_mov_b32_e32 v87, 0
	s_nop 0
	v_cndmask_b32_e64 v84, v20, v84, s[16:17]
	v_ashrrev_i32_e32 v86, 7, v84
	v_ashrrev_i32_e32 v88, 15, v84
	v_lshlrev_b64 v[160:161], 13, v[86:87]
	v_lshlrev_b64 v[164:165], 7, v[86:87]
	v_lshl_add_u64 v[160:161], v[2:3], 0, v[160:161]
	v_lshl_add_u64 v[164:165], v[4:5], 0, v[164:165]
	v_lshl_add_u64 v[162:163], v[160:161], 0, s[6:7]
	global_load_dwordx4 v[64:67], v[160:161], off
	global_load_dword v80, v[164:165], off
	global_load_dwordx4 v[68:71], v[160:161], off offset:2048
	global_load_dword v81, v[164:165], off offset:32
	global_load_dwordx4 v[72:75], v[162:163], off
	global_load_dword v82, v[164:165], off offset:64
	global_load_dwordx4 v[76:79], v[162:163], off offset:2048
	global_load_dword v83, v[164:165], off offset:96
	v_add_u32_e32 v116, s12, v20
	s_add_i32 s12, s12, s11
	v_cmp_gt_i32_e64 s[18:19], s10, v116
	v_mov_b32_e32 v119, 0
	s_nop 0
	v_cndmask_b32_e64 v116, v20, v116, s[18:19]
	v_ashrrev_i32_e32 v118, 7, v116
	v_ashrrev_i32_e32 v120, 15, v116
	v_lshlrev_b64 v[160:161], 13, v[118:119]
	v_lshlrev_b64 v[164:165], 7, v[118:119]
	v_lshl_add_u64 v[160:161], v[2:3], 0, v[160:161]
	v_lshl_add_u64 v[164:165], v[4:5], 0, v[164:165]
	v_lshl_add_u64 v[162:163], v[160:161], 0, s[6:7]
	global_load_dwordx4 v[96:99], v[160:161], off
	global_load_dword v112, v[164:165], off
	global_load_dwordx4 v[100:103], v[160:161], off offset:2048
	global_load_dword v113, v[164:165], off offset:32
	global_load_dwordx4 v[104:107], v[162:163], off
	global_load_dword v114, v[164:165], off offset:64
	global_load_dwordx4 v[108:111], v[162:163], off offset:2048
	global_load_dword v115, v[164:165], off offset:96
	v_add_u32_e32 v148, s12, v20
	v_cmp_gt_i32_e64 s[20:21], s10, v148
	v_mov_b32_e32 v151, 0
	s_nop 0
	v_cndmask_b32_e64 v148, v20, v148, s[20:21]
	v_ashrrev_i32_e32 v150, 7, v148
	v_ashrrev_i32_e32 v152, 15, v148
	v_lshlrev_b64 v[160:161], 13, v[150:151]
	v_lshlrev_b64 v[164:165], 7, v[150:151]
	v_lshl_add_u64 v[160:161], v[2:3], 0, v[160:161]
	v_lshl_add_u64 v[164:165], v[4:5], 0, v[164:165]
	v_lshl_add_u64 v[162:163], v[160:161], 0, s[6:7]
	global_load_dwordx4 v[128:131], v[160:161], off
	global_load_dword v144, v[164:165], off
	global_load_dwordx4 v[132:135], v[160:161], off offset:2048
	global_load_dword v145, v[164:165], off offset:32
	global_load_dwordx4 v[136:139], v[162:163], off
	global_load_dword v146, v[164:165], off offset:64
	global_load_dwordx4 v[140:143], v[162:163], off offset:2048
	global_load_dword v147, v[164:165], off offset:96
	s_waitcnt vmcnt(24)
	v_cmp_lt_i32_e64 s[8:9], 0, v56
	v_cmp_lt_i32_e64 s[22:23], 1, v56
	v_cmp_lt_i32_e64 s[24:25], 2, v56
	v_mov_b32_e32 v8, 0
	v_mov_b32_e32 v9, 0
	v_mov_b32_e32 v10, 0
	v_mov_b32_e32 v11, 0
	v_mov_b32_e32 v12, 0
	v_mov_b32_e32 v13, 0
	v_mov_b32_e32 v14, 0
	v_mov_b32_e32 v15, 0
	v_cndmask_b32_e64 v32, 0, v32, s[8:9]
	v_cndmask_b32_e64 v33, 0, v33, s[8:9]
	v_cndmask_b32_e64 v34, 0, v34, s[8:9]
	v_cndmask_b32_e64 v35, 0, v35, s[8:9]
	v_cndmask_b32_e64 v48, 0, v48, s[8:9]
	v_cndmask_b32_e64 v36, 0, v36, s[22:23]
	v_cndmask_b32_e64 v37, 0, v37, s[22:23]
	v_cndmask_b32_e64 v38, 0, v38, s[22:23]
	v_cndmask_b32_e64 v39, 0, v39, s[22:23]
	v_cndmask_b32_e64 v49, 0, v49, s[22:23]
	v_cndmask_b32_e64 v40, 0, v40, s[24:25]
	v_cndmask_b32_e64 v41, 0, v41, s[24:25]
	v_cndmask_b32_e64 v42, 0, v42, s[24:25]
	v_cndmask_b32_e64 v43, 0, v43, s[24:25]
	v_cndmask_b32_e64 v50, 0, v50, s[24:25]
	v_mov_b32_e32 v1, 0
	v_lshlrev_b32_e32 v166, 16, v32
	v_and_b32_e32 v167, 0xffff0000, v32
	v_lshlrev_b32_e32 v168, 16, v33
	v_and_b32_e32 v169, 0xffff0000, v33
	v_lshlrev_b32_e32 v170, 16, v34
	v_and_b32_e32 v171, 0xffff0000, v34
	v_lshlrev_b32_e32 v172, 16, v35
	v_and_b32_e32 v173, 0xffff0000, v35
	v_pk_add_f32 v[8:9], v[8:9], v[166:167]
	v_pk_add_f32 v[10:11], v[10:11], v[168:169]
	v_pk_add_f32 v[12:13], v[12:13], v[170:171]
	v_pk_add_f32 v[14:15], v[14:15], v[172:173]
	v_add_f32_e32 v1, v1, v48
	v_lshlrev_b32_e32 v166, 16, v36
	v_and_b32_e32 v167, 0xffff0000, v36
	v_lshlrev_b32_e32 v168, 16, v37
	v_and_b32_e32 v169, 0xffff0000, v37
	v_lshlrev_b32_e32 v170, 16, v38
	v_and_b32_e32 v171, 0xffff0000, v38
	v_lshlrev_b32_e32 v172, 16, v39
	v_and_b32_e32 v173, 0xffff0000, v39
	v_pk_add_f32 v[8:9], v[8:9], v[166:167]
	v_pk_add_f32 v[10:11], v[10:11], v[168:169]
	v_pk_add_f32 v[12:13], v[12:13], v[170:171]
	v_pk_add_f32 v[14:15], v[14:15], v[172:173]
	v_add_f32_e32 v1, v1, v49
	v_lshlrev_b32_e32 v166, 16, v40
	v_and_b32_e32 v167, 0xffff0000, v40
	v_lshlrev_b32_e32 v168, 16, v41
	v_and_b32_e32 v169, 0xffff0000, v41
	v_lshlrev_b32_e32 v170, 16, v42
	v_and_b32_e32 v171, 0xffff0000, v42
	v_lshlrev_b32_e32 v172, 16, v43
	v_and_b32_e32 v173, 0xffff0000, v43
	v_pk_add_f32 v[8:9], v[8:9], v[166:167]
	v_pk_add_f32 v[10:11], v[10:11], v[168:169]
	v_pk_add_f32 v[12:13], v[12:13], v[170:171]
	v_pk_add_f32 v[14:15], v[14:15], v[172:173]
	v_add_f32_e32 v1, v1, v50
	v_lshlrev_b32_e32 v166, 16, v44
	v_and_b32_e32 v167, 0xffff0000, v44
	v_lshlrev_b32_e32 v168, 16, v45
	v_and_b32_e32 v169, 0xffff0000, v45
	v_lshlrev_b32_e32 v170, 16, v46
	v_and_b32_e32 v171, 0xffff0000, v46
	v_lshlrev_b32_e32 v172, 16, v47
	v_and_b32_e32 v173, 0xffff0000, v47
	v_pk_add_f32 v[8:9], v[8:9], v[166:167]
	v_pk_add_f32 v[10:11], v[10:11], v[168:169]
	v_pk_add_f32 v[12:13], v[12:13], v[170:171]
	v_pk_add_f32 v[14:15], v[14:15], v[172:173]
	v_add_f32_e32 v1, v1, v51
	v_div_scale_f32 v21, s[8:9], v1, v1, 1.0
	v_rcp_f32_e32 v16, v21
	v_div_scale_f32 v28, vcc, 1.0, v1, 1.0
	v_fma_f32 v17, -v21, v16, 1.0
	v_fmac_f32_e32 v16, v17, v16
	v_mul_f32_e32 v17, v28, v16
	v_fma_f32 v22, -v21, v17, v28
	v_fmac_f32_e32 v17, v22, v16
	v_fma_f32 v21, -v21, v17, v28
	v_div_fmas_f32 v16, v21, v16, v17
	v_div_fixup_f32 v16, v16, v1, 1.0
	v_pk_mul_f32 v[8:9], v[16:17], v[8:9] op_sel_hi:[0,1]
	v_pk_mul_f32 v[10:11], v[16:17], v[10:11] op_sel_hi:[0,1]
	v_pk_mul_f32 v[12:13], v[16:17], v[12:13] op_sel_hi:[0,1]
	v_pk_mul_f32 v[14:15], v[16:17], v[14:15] op_sel_hi:[0,1]
	v_lshlrev_b64 v[160:161], 12, v[54:55]
	v_cvt_pk_bf16_f32 v24, v8, v9
	v_cvt_pk_bf16_f32 v25, v10, v11
	v_cvt_pk_bf16_f32 v26, v12, v13
	v_cvt_pk_bf16_f32 v27, v14, v15
	v_lshl_add_u64 v[160:161], v[6:7], 0, v[160:161]
	s_and_saveexec_b64 s[4:5], s[14:15]
	global_store_dwordx4 v[160:161], v[24:27], off
	s_mov_b64 exec, s[4:5]
	s_waitcnt vmcnt(17)
	v_cmp_lt_i32_e64 s[8:9], 0, v88
	v_cmp_lt_i32_e64 s[22:23], 1, v88
	v_cmp_lt_i32_e64 s[24:25], 2, v88
	v_mov_b32_e32 v8, 0
	v_mov_b32_e32 v9, 0
	v_mov_b32_e32 v10, 0
	v_mov_b32_e32 v11, 0
	v_mov_b32_e32 v12, 0
	v_mov_b32_e32 v13, 0
	v_mov_b32_e32 v14, 0
	v_mov_b32_e32 v15, 0
	v_cndmask_b32_e64 v64, 0, v64, s[8:9]
	v_cndmask_b32_e64 v65, 0, v65, s[8:9]
	v_cndmask_b32_e64 v66, 0, v66, s[8:9]
	v_cndmask_b32_e64 v67, 0, v67, s[8:9]
	v_cndmask_b32_e64 v80, 0, v80, s[8:9]
	v_cndmask_b32_e64 v68, 0, v68, s[22:23]
	v_cndmask_b32_e64 v69, 0, v69, s[22:23]
	v_cndmask_b32_e64 v70, 0, v70, s[22:23]
	v_cndmask_b32_e64 v71, 0, v71, s[22:23]
	v_cndmask_b32_e64 v81, 0, v81, s[22:23]
	v_cndmask_b32_e64 v72, 0, v72, s[24:25]
	v_cndmask_b32_e64 v73, 0, v73, s[24:25]
	v_cndmask_b32_e64 v74, 0, v74, s[24:25]
	v_cndmask_b32_e64 v75, 0, v75, s[24:25]
	v_cndmask_b32_e64 v82, 0, v82, s[24:25]
	v_mov_b32_e32 v1, 0
	v_lshlrev_b32_e32 v166, 16, v64
	v_and_b32_e32 v167, 0xffff0000, v64
	v_lshlrev_b32_e32 v168, 16, v65
	v_and_b32_e32 v169, 0xffff0000, v65
	v_lshlrev_b32_e32 v170, 16, v66
	v_and_b32_e32 v171, 0xffff0000, v66
	v_lshlrev_b32_e32 v172, 16, v67
	v_and_b32_e32 v173, 0xffff0000, v67
	v_pk_add_f32 v[8:9], v[8:9], v[166:167]
	v_pk_add_f32 v[10:11], v[10:11], v[168:169]
	v_pk_add_f32 v[12:13], v[12:13], v[170:171]
	v_pk_add_f32 v[14:15], v[14:15], v[172:173]
	v_add_f32_e32 v1, v1, v80
	v_lshlrev_b32_e32 v166, 16, v68
	v_and_b32_e32 v167, 0xffff0000, v68
	v_lshlrev_b32_e32 v168, 16, v69
	v_and_b32_e32 v169, 0xffff0000, v69
	v_lshlrev_b32_e32 v170, 16, v70
	v_and_b32_e32 v171, 0xffff0000, v70
	v_lshlrev_b32_e32 v172, 16, v71
	v_and_b32_e32 v173, 0xffff0000, v71
	v_pk_add_f32 v[8:9], v[8:9], v[166:167]
	v_pk_add_f32 v[10:11], v[10:11], v[168:169]
	v_pk_add_f32 v[12:13], v[12:13], v[170:171]
	v_pk_add_f32 v[14:15], v[14:15], v[172:173]
	v_add_f32_e32 v1, v1, v81
	v_lshlrev_b32_e32 v166, 16, v72
	v_and_b32_e32 v167, 0xffff0000, v72
	v_lshlrev_b32_e32 v168, 16, v73
	v_and_b32_e32 v169, 0xffff0000, v73
	v_lshlrev_b32_e32 v170, 16, v74
	v_and_b32_e32 v171, 0xffff0000, v74
	v_lshlrev_b32_e32 v172, 16, v75
	v_and_b32_e32 v173, 0xffff0000, v75
	v_pk_add_f32 v[8:9], v[8:9], v[166:167]
	v_pk_add_f32 v[10:11], v[10:11], v[168:169]
	v_pk_add_f32 v[12:13], v[12:13], v[170:171]
	v_pk_add_f32 v[14:15], v[14:15], v[172:173]
	v_add_f32_e32 v1, v1, v82
	v_lshlrev_b32_e32 v166, 16, v76
	v_and_b32_e32 v167, 0xffff0000, v76
	v_lshlrev_b32_e32 v168, 16, v77
	v_and_b32_e32 v169, 0xffff0000, v77
	v_lshlrev_b32_e32 v170, 16, v78
	v_and_b32_e32 v171, 0xffff0000, v78
	v_lshlrev_b32_e32 v172, 16, v79
	v_and_b32_e32 v173, 0xffff0000, v79
	v_pk_add_f32 v[8:9], v[8:9], v[166:167]
	v_pk_add_f32 v[10:11], v[10:11], v[168:169]
	v_pk_add_f32 v[12:13], v[12:13], v[170:171]
	v_pk_add_f32 v[14:15], v[14:15], v[172:173]
	v_add_f32_e32 v1, v1, v83
	v_div_scale_f32 v21, s[8:9], v1, v1, 1.0
	v_rcp_f32_e32 v16, v21
	v_div_scale_f32 v28, vcc, 1.0, v1, 1.0
	v_fma_f32 v17, -v21, v16, 1.0
	v_fmac_f32_e32 v16, v17, v16
	v_mul_f32_e32 v17, v28, v16
	v_fma_f32 v22, -v21, v17, v28
	v_fmac_f32_e32 v17, v22, v16
	v_fma_f32 v21, -v21, v17, v28
	v_div_fmas_f32 v16, v21, v16, v17
	v_div_fixup_f32 v16, v16, v1, 1.0
	v_pk_mul_f32 v[8:9], v[16:17], v[8:9] op_sel_hi:[0,1]
	v_pk_mul_f32 v[10:11], v[16:17], v[10:11] op_sel_hi:[0,1]
	v_pk_mul_f32 v[12:13], v[16:17], v[12:13] op_sel_hi:[0,1]
	v_pk_mul_f32 v[14:15], v[16:17], v[14:15] op_sel_hi:[0,1]
	v_lshlrev_b64 v[160:161], 12, v[86:87]
	v_cvt_pk_bf16_f32 v24, v8, v9
	v_cvt_pk_bf16_f32 v25, v10, v11
	v_cvt_pk_bf16_f32 v26, v12, v13
	v_cvt_pk_bf16_f32 v27, v14, v15
	v_lshl_add_u64 v[160:161], v[6:7], 0, v[160:161]
	s_and_saveexec_b64 s[4:5], s[16:17]
	global_store_dwordx4 v[160:161], v[24:27], off
	s_mov_b64 exec, s[4:5]
	s_waitcnt vmcnt(10)
	v_cmp_lt_i32_e64 s[8:9], 0, v120
	v_cmp_lt_i32_e64 s[22:23], 1, v120
	v_cmp_lt_i32_e64 s[24:25], 2, v120
	v_mov_b32_e32 v8, 0
	v_mov_b32_e32 v9, 0
	v_mov_b32_e32 v10, 0
	v_mov_b32_e32 v11, 0
	v_mov_b32_e32 v12, 0
	v_mov_b32_e32 v13, 0
	v_mov_b32_e32 v14, 0
	v_mov_b32_e32 v15, 0
	v_cndmask_b32_e64 v96, 0, v96, s[8:9]
	v_cndmask_b32_e64 v97, 0, v97, s[8:9]
	v_cndmask_b32_e64 v98, 0, v98, s[8:9]
	v_cndmask_b32_e64 v99, 0, v99, s[8:9]
	v_cndmask_b32_e64 v112, 0, v112, s[8:9]
	v_cndmask_b32_e64 v100, 0, v100, s[22:23]
	v_cndmask_b32_e64 v101, 0, v101, s[22:23]
	v_cndmask_b32_e64 v102, 0, v102, s[22:23]
	v_cndmask_b32_e64 v103, 0, v103, s[22:23]
	v_cndmask_b32_e64 v113, 0, v113, s[22:23]
	v_cndmask_b32_e64 v104, 0, v104, s[24:25]
	v_cndmask_b32_e64 v105, 0, v105, s[24:25]
	v_cndmask_b32_e64 v106, 0, v106, s[24:25]
	v_cndmask_b32_e64 v107, 0, v107, s[24:25]
	v_cndmask_b32_e64 v114, 0, v114, s[24:25]
	v_mov_b32_e32 v1, 0
	v_lshlrev_b32_e32 v166, 16, v96
	v_and_b32_e32 v167, 0xffff0000, v96
	v_lshlrev_b32_e32 v168, 16, v97
	v_and_b32_e32 v169, 0xffff0000, v97
	v_lshlrev_b32_e32 v170, 16, v98
	v_and_b32_e32 v171, 0xffff0000, v98
	v_lshlrev_b32_e32 v172, 16, v99
	v_and_b32_e32 v173, 0xffff0000, v99
	v_pk_add_f32 v[8:9], v[8:9], v[166:167]
	v_pk_add_f32 v[10:11], v[10:11], v[168:169]
	v_pk_add_f32 v[12:13], v[12:13], v[170:171]
	v_pk_add_f32 v[14:15], v[14:15], v[172:173]
	v_add_f32_e32 v1, v1, v112
	v_lshlrev_b32_e32 v166, 16, v100
	v_and_b32_e32 v167, 0xffff0000, v100
	v_lshlrev_b32_e32 v168, 16, v101
	v_and_b32_e32 v169, 0xffff0000, v101
	v_lshlrev_b32_e32 v170, 16, v102
	v_and_b32_e32 v171, 0xffff0000, v102
	v_lshlrev_b32_e32 v172, 16, v103
	v_and_b32_e32 v173, 0xffff0000, v103
	v_pk_add_f32 v[8:9], v[8:9], v[166:167]
	v_pk_add_f32 v[10:11], v[10:11], v[168:169]
	v_pk_add_f32 v[12:13], v[12:13], v[170:171]
	v_pk_add_f32 v[14:15], v[14:15], v[172:173]
	v_add_f32_e32 v1, v1, v113
	v_lshlrev_b32_e32 v166, 16, v104
	v_and_b32_e32 v167, 0xffff0000, v104
	v_lshlrev_b32_e32 v168, 16, v105
	v_and_b32_e32 v169, 0xffff0000, v105
	v_lshlrev_b32_e32 v170, 16, v106
	v_and_b32_e32 v171, 0xffff0000, v106
	v_lshlrev_b32_e32 v172, 16, v107
	v_and_b32_e32 v173, 0xffff0000, v107
	v_pk_add_f32 v[8:9], v[8:9], v[166:167]
	v_pk_add_f32 v[10:11], v[10:11], v[168:169]
	v_pk_add_f32 v[12:13], v[12:13], v[170:171]
	v_pk_add_f32 v[14:15], v[14:15], v[172:173]
	v_add_f32_e32 v1, v1, v114
	v_lshlrev_b32_e32 v166, 16, v108
	v_and_b32_e32 v167, 0xffff0000, v108
	v_lshlrev_b32_e32 v168, 16, v109
	v_and_b32_e32 v169, 0xffff0000, v109
	v_lshlrev_b32_e32 v170, 16, v110
	v_and_b32_e32 v171, 0xffff0000, v110
	v_lshlrev_b32_e32 v172, 16, v111
	v_and_b32_e32 v173, 0xffff0000, v111
	v_pk_add_f32 v[8:9], v[8:9], v[166:167]
	v_pk_add_f32 v[10:11], v[10:11], v[168:169]
	v_pk_add_f32 v[12:13], v[12:13], v[170:171]
	v_pk_add_f32 v[14:15], v[14:15], v[172:173]
	v_add_f32_e32 v1, v1, v115
	v_div_scale_f32 v21, s[8:9], v1, v1, 1.0
	v_rcp_f32_e32 v16, v21
	v_div_scale_f32 v28, vcc, 1.0, v1, 1.0
	v_fma_f32 v17, -v21, v16, 1.0
	v_fmac_f32_e32 v16, v17, v16
	v_mul_f32_e32 v17, v28, v16
	v_fma_f32 v22, -v21, v17, v28
	v_fmac_f32_e32 v17, v22, v16
	v_fma_f32 v21, -v21, v17, v28
	v_div_fmas_f32 v16, v21, v16, v17
	v_div_fixup_f32 v16, v16, v1, 1.0
	v_pk_mul_f32 v[8:9], v[16:17], v[8:9] op_sel_hi:[0,1]
	v_pk_mul_f32 v[10:11], v[16:17], v[10:11] op_sel_hi:[0,1]
	v_pk_mul_f32 v[12:13], v[16:17], v[12:13] op_sel_hi:[0,1]
	v_pk_mul_f32 v[14:15], v[16:17], v[14:15] op_sel_hi:[0,1]
	v_lshlrev_b64 v[160:161], 12, v[118:119]
	v_cvt_pk_bf16_f32 v24, v8, v9
	v_cvt_pk_bf16_f32 v25, v10, v11
	v_cvt_pk_bf16_f32 v26, v12, v13
	v_cvt_pk_bf16_f32 v27, v14, v15
	v_lshl_add_u64 v[160:161], v[6:7], 0, v[160:161]
	s_and_saveexec_b64 s[4:5], s[18:19]
	global_store_dwordx4 v[160:161], v[24:27], off
	s_mov_b64 exec, s[4:5]
	s_waitcnt vmcnt(3)
	v_cmp_lt_i32_e64 s[8:9], 0, v152
	v_cmp_lt_i32_e64 s[22:23], 1, v152
	v_cmp_lt_i32_e64 s[24:25], 2, v152
	v_mov_b32_e32 v8, 0
	v_mov_b32_e32 v9, 0
	v_mov_b32_e32 v10, 0
	v_mov_b32_e32 v11, 0
	v_mov_b32_e32 v12, 0
	v_mov_b32_e32 v13, 0
	v_mov_b32_e32 v14, 0
	v_mov_b32_e32 v15, 0
	v_cndmask_b32_e64 v128, 0, v128, s[8:9]
	v_cndmask_b32_e64 v129, 0, v129, s[8:9]
	v_cndmask_b32_e64 v130, 0, v130, s[8:9]
	v_cndmask_b32_e64 v131, 0, v131, s[8:9]
	v_cndmask_b32_e64 v144, 0, v144, s[8:9]
	v_cndmask_b32_e64 v132, 0, v132, s[22:23]
	v_cndmask_b32_e64 v133, 0, v133, s[22:23]
	v_cndmask_b32_e64 v134, 0, v134, s[22:23]
	v_cndmask_b32_e64 v135, 0, v135, s[22:23]
	v_cndmask_b32_e64 v145, 0, v145, s[22:23]
	v_cndmask_b32_e64 v136, 0, v136, s[24:25]
	v_cndmask_b32_e64 v137, 0, v137, s[24:25]
	v_cndmask_b32_e64 v138, 0, v138, s[24:25]
	v_cndmask_b32_e64 v139, 0, v139, s[24:25]
	v_cndmask_b32_e64 v146, 0, v146, s[24:25]
	v_mov_b32_e32 v1, 0
	v_lshlrev_b32_e32 v166, 16, v128
	v_and_b32_e32 v167, 0xffff0000, v128
	v_lshlrev_b32_e32 v168, 16, v129
	v_and_b32_e32 v169, 0xffff0000, v129
	v_lshlrev_b32_e32 v170, 16, v130
	v_and_b32_e32 v171, 0xffff0000, v130
	v_lshlrev_b32_e32 v172, 16, v131
	v_and_b32_e32 v173, 0xffff0000, v131
	v_pk_add_f32 v[8:9], v[8:9], v[166:167]
	v_pk_add_f32 v[10:11], v[10:11], v[168:169]
	v_pk_add_f32 v[12:13], v[12:13], v[170:171]
	v_pk_add_f32 v[14:15], v[14:15], v[172:173]
	v_add_f32_e32 v1, v1, v144
	v_lshlrev_b32_e32 v166, 16, v132
	v_and_b32_e32 v167, 0xffff0000, v132
	v_lshlrev_b32_e32 v168, 16, v133
	v_and_b32_e32 v169, 0xffff0000, v133
	v_lshlrev_b32_e32 v170, 16, v134
	v_and_b32_e32 v171, 0xffff0000, v134
	v_lshlrev_b32_e32 v172, 16, v135
	v_and_b32_e32 v173, 0xffff0000, v135
	v_pk_add_f32 v[8:9], v[8:9], v[166:167]
	v_pk_add_f32 v[10:11], v[10:11], v[168:169]
	v_pk_add_f32 v[12:13], v[12:13], v[170:171]
	v_pk_add_f32 v[14:15], v[14:15], v[172:173]
	v_add_f32_e32 v1, v1, v145
	v_lshlrev_b32_e32 v166, 16, v136
	v_and_b32_e32 v167, 0xffff0000, v136
	v_lshlrev_b32_e32 v168, 16, v137
	v_and_b32_e32 v169, 0xffff0000, v137
	v_lshlrev_b32_e32 v170, 16, v138
	v_and_b32_e32 v171, 0xffff0000, v138
	v_lshlrev_b32_e32 v172, 16, v139
	v_and_b32_e32 v173, 0xffff0000, v139
	v_pk_add_f32 v[8:9], v[8:9], v[166:167]
	v_pk_add_f32 v[10:11], v[10:11], v[168:169]
	v_pk_add_f32 v[12:13], v[12:13], v[170:171]
	v_pk_add_f32 v[14:15], v[14:15], v[172:173]
	v_add_f32_e32 v1, v1, v146
	v_lshlrev_b32_e32 v166, 16, v140
	v_and_b32_e32 v167, 0xffff0000, v140
	v_lshlrev_b32_e32 v168, 16, v141
	v_and_b32_e32 v169, 0xffff0000, v141
	v_lshlrev_b32_e32 v170, 16, v142
	v_and_b32_e32 v171, 0xffff0000, v142
	v_lshlrev_b32_e32 v172, 16, v143
	v_and_b32_e32 v173, 0xffff0000, v143
	v_pk_add_f32 v[8:9], v[8:9], v[166:167]
	v_pk_add_f32 v[10:11], v[10:11], v[168:169]
	v_pk_add_f32 v[12:13], v[12:13], v[170:171]
	v_pk_add_f32 v[14:15], v[14:15], v[172:173]
	v_add_f32_e32 v1, v1, v147
	v_div_scale_f32 v21, s[8:9], v1, v1, 1.0
	v_rcp_f32_e32 v16, v21
	v_div_scale_f32 v28, vcc, 1.0, v1, 1.0
	v_fma_f32 v17, -v21, v16, 1.0
	v_fmac_f32_e32 v16, v17, v16
	v_mul_f32_e32 v17, v28, v16
	v_fma_f32 v22, -v21, v17, v28
	v_fmac_f32_e32 v17, v22, v16
	v_fma_f32 v21, -v21, v17, v28
	v_div_fmas_f32 v16, v21, v16, v17
	v_div_fixup_f32 v16, v16, v1, 1.0
	v_pk_mul_f32 v[8:9], v[16:17], v[8:9] op_sel_hi:[0,1]
	v_pk_mul_f32 v[10:11], v[16:17], v[10:11] op_sel_hi:[0,1]
	v_pk_mul_f32 v[12:13], v[16:17], v[12:13] op_sel_hi:[0,1]
	v_pk_mul_f32 v[14:15], v[16:17], v[14:15] op_sel_hi:[0,1]
	v_lshlrev_b64 v[160:161], 12, v[150:151]
	v_cvt_pk_bf16_f32 v24, v8, v9
	v_cvt_pk_bf16_f32 v25, v10, v11
	v_cvt_pk_bf16_f32 v26, v12, v13
	v_cvt_pk_bf16_f32 v27, v14, v15
	v_lshl_add_u64 v[160:161], v[6:7], 0, v[160:161]
	s_and_saveexec_b64 s[4:5], s[20:21]
	global_store_dwordx4 v[160:161], v[24:27], off
	s_mov_b64 exec, s[4:5]
	s_lshl_b32 s12, s11, 2
	v_add_u32_e32 v20, s12, v20
	v_cmp_le_i32_e32 vcc, s10, v20
	s_or_b64 s[2:3], vcc, s[2:3]
	s_andn2_b64 exec, exec, s[2:3]
	s_cbranch_execnz .Lc4_outer
